# idle-CU L2 warming: in the last GEMM phase (32 single-unit workgroups, 224 idle) the idle workgroups of each XCD touch the K-slices of that XCD's units once so the units' staging loads hit L2
# baseline (speedup 1.0000x reference)
; #define OUTP() ((float*)tab_get(lds, 30))
; #define WSB(off) ((bf16*)((unsigned char*)tab_get(lds, 31) + (off)))
; __global__ void __launch_bounds__(512, 2) mega_fwd(Params p) {
;     ...
; #pragma unroll 1
;         for (int pc = 0; pc < 4; ++pc) { const int k0 = pc < 2 ? 768 * pc : 1536 + 640 * (pc - 2), kl = pc < 2 ? 768 : 640;
;             pg8::Gemm g{WSB(WS_ACT) + SROWS * NFF + k0, WSB(WS_WDN) + k0, MS, 1024, kl, NFF, NFF}; pg8::StaticOrder S; S.init(MS, 1024, G, (bx + G - 8 * pc) % G); pg8::EpiAtomicAdd E{OUTP() + SROWS * DM}; pg8::gemm_phase(lds, g, S, E); }
.LBB0_1765:
	s_or_b64 exec, exec, s[34:35]
	s_and_b32 s2, s95, 0xff
	s_cmp_lt_u32 s2, 32
	s_cbranch_scc1 .Lwarm_skip
	s_and_b32 s3, s2, 31
	s_lshr_b32 s4, s2, 5
	s_sub_u32 s4, s4, 1
	s_lshr_b32 s5, s3, 3
	s_and_b32 s6, s3, 7
	s_and_b32 s7, s6, 1
	s_lshr_b32 s6, s6, 1
	s_mul_i32 s8, s5, 0x600
	s_cmp_eq_u32 s5, 3
	s_cselect_b32 s8, 0x1100, s8
	s_lshl_b32 s9, s4, 7
	s_add_u32 s8, s8, s9
	s_getreg_b32 s9, hwreg(HW_REG_HW_ID, 0, 6)
	s_lshl_b32 s9, s9, 2
	s_and_b32 s9, s9, 0xfc
	s_add_i32 s9, s9, 0x25a00
	v_mov_b32_e32 v2, s9
	ds_read_b32 v2, v2
	s_add_i32 s9, 0, 0x258f8
	v_mov_b32_e32 v3, s9
	ds_read_b64 v[0:1], v3
	s_waitcnt lgkmcnt(0)
	v_readfirstlane_b32 s9, v2
	v_readfirstlane_b32 s10, v0
	v_readfirstlane_b32 s11, v1
	s_mul_i32 s12, s7, 0x160000
	s_add_u32 s12, s12, 0x1d200000
	s_mul_i32 s13, s6, 0x160000
	s_add_u32 s13, s13, 0x1c00000
	s_cmp_lt_u32 s9, 4
	s_cselect_b32 s12, s12, s13
	s_add_u32 s12, s12, s8
	s_and_b32 s13, s9, 3
	s_lshl_b32 s13, s13, 6
	v_mbcnt_lo_u32_b32 v0, -1, 0
	v_mbcnt_hi_u32_b32 v0, -1, v0
	v_add_u32_e32 v0, s13, v0
	v_mul_u32_u24_e32 v0, 0x1600, v0
	v_add_u32_e32 v0, s12, v0
	global_load_dword v1, v0, s[10:11]
	s_cmp_gt_u32 s4, 4
	s_cbranch_scc1 .Lwarm_one
	global_load_dword v2, v0, s[10:11] offset:896

; #define OUTP() ((float*)tab_get(lds, 30))
; #define WSB(off) ((bf16*)((unsigned char*)tab_get(lds, 31) + (off)))
; __global__ void __launch_bounds__(512, 2) mega_fwd(Params p) {
;     ...
; #pragma unroll 1
;         for (int pc = 0; pc < 4; ++pc) { const int k0 = pc < 2 ? 768 * pc : 1536 + 640 * (pc - 2), kl = pc < 2 ? 768 : 640;
;             pg8::Gemm g{WSB(WS_ACT) + SROWS * NFF + k0, WSB(WS_WDN) + k0, MS, 1024, kl, NFF, NFF}; pg8::StaticOrder S; S.init(MS, 1024, G, (bx + G - 8 * pc) % G); pg8::EpiAtomicAdd E{OUTP() + SROWS * DM}; pg8::gemm_phase(lds, g, S, E); }
.Lwarm_skip:
	s_add_i32 s2, 0, 0x258f8
	v_mov_b32_e32 v140, s2
	s_add_i32 s2, 0, 0x258f0
	s_mov_b32 s5, 0
	v_mov_b32_e32 v141, s2
	s_mov_b32 s33, 0xffffe0
	s_movk_i32 s37, 0xb00
	v_mov_b32_e32 v129, 0
	s_mov_b64 s[6:7], 0xb0000
	s_mov_b64 s[8:9], 0x80
	s_mov_b64 s[10:11], 0xb0080
	s_mov_b32 s40, 0xb000
	s_mov_b64 s[12:13], 0x80000
	s_mov_b32 s41, 0x80000
	s_mov_b64 s[14:15], 0x90000
	s_mov_b32 s42, 0x90000
	s_mov_b64 s[16:17], 0xa0000
	s_mov_b32 s43, 0xa0000
	s_mov_b32 s45, 0xb0000
	v_mov_b32_e32 v142, 1
	s_mov_b32 s46, 0
	s_waitcnt lgkmcnt(0)
	s_barrier
	s_branch .LBB0_1768
